# gemm_small inner loops software-pipelined: 4-stage global_load ring with counted vmcnt instead of flat_load+vmcnt(0) per fragment
# speedup vs baseline: 1.0053x; 1.0053x over previous
.LBB0_704:
	s_and_b32 s18, s22, 0xffffffc0
	v_or_b32_e32 v2, s18, v174
	v_lshlrev_b32_e32 v4, 1, v2
	v_or_b32_e32 v5, 0x60, v4
	v_mov_b64_e32 v[0:1], s[8:9]
	v_mad_u64_u32 v[64:65], s[18:19], s61, v5, v[0:1]
	v_or_b32_e32 v5, 64, v4
	v_or_b32_e32 v4, 32, v4
	v_mad_u64_u32 v[66:67], s[18:19], s61, v5, v[0:1]
	v_mad_u64_u32 v[68:69], s[18:19], s61, v4, v[0:1]
	v_mad_i64_i32 v[70:71], s[18:19], s21, v2, v[0:1]
	s_lshl_b32 s18, s23, 6
	s_and_b32 s18, s18, 0x3c0
	v_or_b32_e32 v0, s18, v174
	v_mul_u32_u24_e32 v152, s61, v0
	v_lshl_add_u64 v[0:1], s[4:5], 0, v[152:153]
	v_lshlrev_b64 v[0:1], 1, v[0:1]
	v_ashrrev_i32_e32 v3, 31, v2
	v_lshl_add_u64 v[72:73], s[10:11], 0, v[0:1]
	v_lshl_add_u64 v[74:75], s[12:13], 0, v[0:1]
	v_lshl_add_u64 v[76:77], s[14:15], 0, v[0:1]
	v_lshlrev_b32_e32 v152, 1, v152
	v_mov_b32_e32 v0, 0
	v_mad_i32_i24 v65, s61, v3, v65
	v_mad_i32_i24 v67, s61, v3, v67
	v_mad_i32_i24 v69, s61, v3, v69
	v_lshl_add_u64 v[78:79], s[16:17], 0, v[152:153]
	s_mov_b32 s19, s20
	v_mov_b32_e32 v1, v0
	v_mov_b32_e32 v2, v0
	v_mov_b32_e32 v3, v0
	v_mov_b32_e32 v4, v0
	v_mov_b32_e32 v5, v0
	v_mov_b32_e32 v6, v0
	v_mov_b32_e32 v7, v0
	v_mov_b32_e32 v8, v0
	v_mov_b32_e32 v9, v0
	v_mov_b32_e32 v10, v0
	v_mov_b32_e32 v11, v0
	v_mov_b32_e32 v12, v0
	v_mov_b32_e32 v13, v0
	v_mov_b32_e32 v14, v0
	v_mov_b32_e32 v15, v0
	v_mov_b32_e32 v16, v0
	v_mov_b32_e32 v17, v0
	v_mov_b32_e32 v18, v0
	v_mov_b32_e32 v19, v0
	v_mov_b32_e32 v20, v0
	v_mov_b32_e32 v21, v0
	v_mov_b32_e32 v22, v0
	v_mov_b32_e32 v23, v0
	v_mov_b32_e32 v24, v0
	v_mov_b32_e32 v25, v0
	v_mov_b32_e32 v26, v0
	v_mov_b32_e32 v27, v0
	v_mov_b32_e32 v36, v0
	v_mov_b32_e32 v37, v0
	v_mov_b32_e32 v38, v0
	v_mov_b32_e32 v39, v0
	v_mov_b32_e32 v28, v0
	v_mov_b32_e32 v29, v0
	v_mov_b32_e32 v30, v0
	v_mov_b32_e32 v31, v0
	v_mov_b32_e32 v32, v0
	v_mov_b32_e32 v33, v0
	v_mov_b32_e32 v34, v0
	v_mov_b32_e32 v35, v0
	v_mov_b32_e32 v40, v0
	v_mov_b32_e32 v41, v0
	v_mov_b32_e32 v42, v0
	v_mov_b32_e32 v43, v0
	v_mov_b32_e32 v44, v0
	v_mov_b32_e32 v45, v0
	v_mov_b32_e32 v46, v0
	v_mov_b32_e32 v47, v0
	v_mov_b32_e32 v48, v0
	v_mov_b32_e32 v49, v0
	v_mov_b32_e32 v50, v0
	v_mov_b32_e32 v51, v0
	v_mov_b32_e32 v52, v0
	v_mov_b32_e32 v53, v0
	v_mov_b32_e32 v54, v0
	v_mov_b32_e32 v55, v0
	v_mov_b32_e32 v56, v0
	v_mov_b32_e32 v57, v0
	v_mov_b32_e32 v58, v0
	v_mov_b32_e32 v59, v0
	v_mov_b32_e32 v60, v0
	v_mov_b32_e32 v61, v0
	v_mov_b32_e32 v62, v0
	v_mov_b32_e32 v63, v0
	v_lshl_add_u64 v[70:71], v[70:71], 0, v[88:89]
	v_lshl_add_u64 v[68:69], v[68:69], 0, v[88:89]
	v_lshl_add_u64 v[66:67], v[66:67], 0, v[88:89]
	v_lshl_add_u64 v[64:65], v[64:65], 0, v[88:89]
	v_lshl_add_u64 v[78:79], v[78:79], 0, v[88:89]
	v_lshl_add_u64 v[76:77], v[76:77], 0, v[88:89]
	v_lshl_add_u64 v[74:75], v[74:75], 0, v[88:89]
	v_lshl_add_u64 v[72:73], v[72:73], 0, v[88:89]
	v_mov_b32_e32 v250, 0x100
	v_mov_b32_e32 v251, 0
	global_load_dwordx4 v[80:83], v[70:71], off
	global_load_dwordx4 v[84:87], v[68:69], off
	global_load_dwordx4 v[90:93], v[66:67], off
	global_load_dwordx4 v[108:111], v[64:65], off
	global_load_dwordx4 v[112:115], v[78:79], off
	global_load_dwordx4 v[116:119], v[76:77], off
	global_load_dwordx4 v[120:123], v[74:75], off
	global_load_dwordx4 v[124:127], v[72:73], off
	global_load_dwordx4 v[128:131], v[70:71], off offset:64
	global_load_dwordx4 v[132:135], v[68:69], off offset:64
	global_load_dwordx4 v[136:139], v[66:67], off offset:64
	global_load_dwordx4 v[140:143], v[64:65], off offset:64
	global_load_dwordx4 v[144:147], v[78:79], off offset:64
	global_load_dwordx4 v[158:161], v[76:77], off offset:64
	global_load_dwordx4 v[162:165], v[74:75], off offset:64
	global_load_dwordx4 v[166:169], v[72:73], off offset:64
	global_load_dwordx4 v[170:173], v[70:71], off offset:128
	global_load_dwordx4 v[178:181], v[68:69], off offset:128
	global_load_dwordx4 v[194:197], v[66:67], off offset:128
	global_load_dwordx4 v[198:201], v[64:65], off offset:128
	global_load_dwordx4 v[202:205], v[78:79], off offset:128
	global_load_dwordx4 v[206:209], v[76:77], off offset:128
	global_load_dwordx4 v[210:213], v[74:75], off offset:128
	global_load_dwordx4 v[214:217], v[72:73], off offset:128
	global_load_dwordx4 v[218:221], v[70:71], off offset:192
	global_load_dwordx4 v[222:225], v[68:69], off offset:192
	global_load_dwordx4 v[226:229], v[66:67], off offset:192
	global_load_dwordx4 v[230:233], v[64:65], off offset:192
	global_load_dwordx4 v[234:237], v[78:79], off offset:192
	global_load_dwordx4 v[238:241], v[76:77], off offset:192
	global_load_dwordx4 v[242:245], v[74:75], off offset:192
	global_load_dwordx4 v[246:249], v[72:73], off offset:192
	s_lshr_b32 s19, s19, 2
	s_add_i32 s19, s19, -1
.Lgsa_loop:
	s_cmp_eq_u32 s19, 0
	s_cbranch_scc1 .Lgsa_tail
	s_waitcnt vmcnt(24)
	v_mfma_f32_16x16x32_bf16 v[36:39], v[80:83], v[112:115], v[36:39]
	v_mfma_f32_16x16x32_bf16 v[24:27], v[84:87], v[112:115], v[24:27]
	v_mfma_f32_16x16x32_bf16 v[20:23], v[90:93], v[112:115], v[20:23]
	v_mfma_f32_16x16x32_bf16 v[16:19], v[108:111], v[112:115], v[16:19]
	v_mfma_f32_16x16x32_bf16 v[12:15], v[80:83], v[116:119], v[12:15]
	v_mfma_f32_16x16x32_bf16 v[8:11], v[84:87], v[116:119], v[8:11]
	v_mfma_f32_16x16x32_bf16 v[4:7], v[90:93], v[116:119], v[4:7]
	v_mfma_f32_16x16x32_bf16 v[0:3], v[108:111], v[116:119], v[0:3]
	v_mfma_f32_16x16x32_bf16 v[28:31], v[80:83], v[120:123], v[28:31]
	v_mfma_f32_16x16x32_bf16 v[32:35], v[84:87], v[120:123], v[32:35]
	v_mfma_f32_16x16x32_bf16 v[40:43], v[90:93], v[120:123], v[40:43]
	v_mfma_f32_16x16x32_bf16 v[44:47], v[108:111], v[120:123], v[44:47]
	v_mfma_f32_16x16x32_bf16 v[48:51], v[80:83], v[124:127], v[48:51]
	v_mfma_f32_16x16x32_bf16 v[52:55], v[84:87], v[124:127], v[52:55]
	v_mfma_f32_16x16x32_bf16 v[56:59], v[90:93], v[124:127], v[56:59]
	v_mfma_f32_16x16x32_bf16 v[60:63], v[108:111], v[124:127], v[60:63]
	global_load_dwordx4 v[80:83], v[70:71], off offset:256
	global_load_dwordx4 v[84:87], v[68:69], off offset:256
	global_load_dwordx4 v[90:93], v[66:67], off offset:256
	global_load_dwordx4 v[108:111], v[64:65], off offset:256
	global_load_dwordx4 v[112:115], v[78:79], off offset:256
	global_load_dwordx4 v[116:119], v[76:77], off offset:256
	global_load_dwordx4 v[120:123], v[74:75], off offset:256
	global_load_dwordx4 v[124:127], v[72:73], off offset:256
	s_waitcnt vmcnt(24)
	v_mfma_f32_16x16x32_bf16 v[36:39], v[128:131], v[144:147], v[36:39]
	v_mfma_f32_16x16x32_bf16 v[24:27], v[132:135], v[144:147], v[24:27]
	v_mfma_f32_16x16x32_bf16 v[20:23], v[136:139], v[144:147], v[20:23]
	v_mfma_f32_16x16x32_bf16 v[16:19], v[140:143], v[144:147], v[16:19]
	v_mfma_f32_16x16x32_bf16 v[12:15], v[128:131], v[158:161], v[12:15]
	v_mfma_f32_16x16x32_bf16 v[8:11], v[132:135], v[158:161], v[8:11]
	v_mfma_f32_16x16x32_bf16 v[4:7], v[136:139], v[158:161], v[4:7]
	v_mfma_f32_16x16x32_bf16 v[0:3], v[140:143], v[158:161], v[0:3]
	v_mfma_f32_16x16x32_bf16 v[28:31], v[128:131], v[162:165], v[28:31]
	v_mfma_f32_16x16x32_bf16 v[32:35], v[132:135], v[162:165], v[32:35]
	v_mfma_f32_16x16x32_bf16 v[40:43], v[136:139], v[162:165], v[40:43]
	v_mfma_f32_16x16x32_bf16 v[44:47], v[140:143], v[162:165], v[44:47]
	v_mfma_f32_16x16x32_bf16 v[48:51], v[128:131], v[166:169], v[48:51]
	v_mfma_f32_16x16x32_bf16 v[52:55], v[132:135], v[166:169], v[52:55]
	v_mfma_f32_16x16x32_bf16 v[56:59], v[136:139], v[166:169], v[56:59]
	v_mfma_f32_16x16x32_bf16 v[60:63], v[140:143], v[166:169], v[60:63]
	global_load_dwordx4 v[128:131], v[70:71], off offset:320
	global_load_dwordx4 v[132:135], v[68:69], off offset:320
	global_load_dwordx4 v[136:139], v[66:67], off offset:320
	global_load_dwordx4 v[140:143], v[64:65], off offset:320
	global_load_dwordx4 v[144:147], v[78:79], off offset:320
	global_load_dwordx4 v[158:161], v[76:77], off offset:320
	global_load_dwordx4 v[162:165], v[74:75], off offset:320
	global_load_dwordx4 v[166:169], v[72:73], off offset:320
	s_waitcnt vmcnt(24)
	v_mfma_f32_16x16x32_bf16 v[36:39], v[170:173], v[202:205], v[36:39]
	v_mfma_f32_16x16x32_bf16 v[24:27], v[178:181], v[202:205], v[24:27]
	v_mfma_f32_16x16x32_bf16 v[20:23], v[194:197], v[202:205], v[20:23]
	v_mfma_f32_16x16x32_bf16 v[16:19], v[198:201], v[202:205], v[16:19]
	v_mfma_f32_16x16x32_bf16 v[12:15], v[170:173], v[206:209], v[12:15]
	v_mfma_f32_16x16x32_bf16 v[8:11], v[178:181], v[206:209], v[8:11]
	v_mfma_f32_16x16x32_bf16 v[4:7], v[194:197], v[206:209], v[4:7]
	v_mfma_f32_16x16x32_bf16 v[0:3], v[198:201], v[206:209], v[0:3]
	v_mfma_f32_16x16x32_bf16 v[28:31], v[170:173], v[210:213], v[28:31]
	v_mfma_f32_16x16x32_bf16 v[32:35], v[178:181], v[210:213], v[32:35]
	v_mfma_f32_16x16x32_bf16 v[40:43], v[194:197], v[210:213], v[40:43]
	v_mfma_f32_16x16x32_bf16 v[44:47], v[198:201], v[210:213], v[44:47]
	v_mfma_f32_16x16x32_bf16 v[48:51], v[170:173], v[214:217], v[48:51]
	v_mfma_f32_16x16x32_bf16 v[52:55], v[178:181], v[214:217], v[52:55]
	v_mfma_f32_16x16x32_bf16 v[56:59], v[194:197], v[214:217], v[56:59]
	v_mfma_f32_16x16x32_bf16 v[60:63], v[198:201], v[214:217], v[60:63]
	global_load_dwordx4 v[170:173], v[70:71], off offset:384
	global_load_dwordx4 v[178:181], v[68:69], off offset:384
	global_load_dwordx4 v[194:197], v[66:67], off offset:384
	global_load_dwordx4 v[198:201], v[64:65], off offset:384
	global_load_dwordx4 v[202:205], v[78:79], off offset:384
	global_load_dwordx4 v[206:209], v[76:77], off offset:384
	global_load_dwordx4 v[210:213], v[74:75], off offset:384
	global_load_dwordx4 v[214:217], v[72:73], off offset:384
	s_waitcnt vmcnt(24)
	v_mfma_f32_16x16x32_bf16 v[36:39], v[218:221], v[234:237], v[36:39]
	v_mfma_f32_16x16x32_bf16 v[24:27], v[222:225], v[234:237], v[24:27]
	v_mfma_f32_16x16x32_bf16 v[20:23], v[226:229], v[234:237], v[20:23]
	v_mfma_f32_16x16x32_bf16 v[16:19], v[230:233], v[234:237], v[16:19]
	v_mfma_f32_16x16x32_bf16 v[12:15], v[218:221], v[238:241], v[12:15]
	v_mfma_f32_16x16x32_bf16 v[8:11], v[222:225], v[238:241], v[8:11]
	v_mfma_f32_16x16x32_bf16 v[4:7], v[226:229], v[238:241], v[4:7]
	v_mfma_f32_16x16x32_bf16 v[0:3], v[230:233], v[238:241], v[0:3]
	v_mfma_f32_16x16x32_bf16 v[28:31], v[218:221], v[242:245], v[28:31]
	v_mfma_f32_16x16x32_bf16 v[32:35], v[222:225], v[242:245], v[32:35]
	v_mfma_f32_16x16x32_bf16 v[40:43], v[226:229], v[242:245], v[40:43]
	v_mfma_f32_16x16x32_bf16 v[44:47], v[230:233], v[242:245], v[44:47]
	v_mfma_f32_16x16x32_bf16 v[48:51], v[218:221], v[246:249], v[48:51]
	v_mfma_f32_16x16x32_bf16 v[52:55], v[222:225], v[246:249], v[52:55]
	v_mfma_f32_16x16x32_bf16 v[56:59], v[226:229], v[246:249], v[56:59]
	v_mfma_f32_16x16x32_bf16 v[60:63], v[230:233], v[246:249], v[60:63]
	global_load_dwordx4 v[218:221], v[70:71], off offset:448
	global_load_dwordx4 v[222:225], v[68:69], off offset:448
	global_load_dwordx4 v[226:229], v[66:67], off offset:448
	global_load_dwordx4 v[230:233], v[64:65], off offset:448
	global_load_dwordx4 v[234:237], v[78:79], off offset:448
	global_load_dwordx4 v[238:241], v[76:77], off offset:448
	global_load_dwordx4 v[242:245], v[74:75], off offset:448
	global_load_dwordx4 v[246:249], v[72:73], off offset:448
	v_lshl_add_u64 v[70:71], v[70:71], 0, v[250:251]
	v_lshl_add_u64 v[68:69], v[68:69], 0, v[250:251]
	v_lshl_add_u64 v[66:67], v[66:67], 0, v[250:251]
	v_lshl_add_u64 v[64:65], v[64:65], 0, v[250:251]
	v_lshl_add_u64 v[78:79], v[78:79], 0, v[250:251]
	v_lshl_add_u64 v[76:77], v[76:77], 0, v[250:251]
	v_lshl_add_u64 v[74:75], v[74:75], 0, v[250:251]
	v_lshl_add_u64 v[72:73], v[72:73], 0, v[250:251]
	s_add_i32 s19, s19, -1
	s_branch .Lgsa_loop
.Lgsa_tail:
	s_waitcnt vmcnt(24)
	v_mfma_f32_16x16x32_bf16 v[36:39], v[80:83], v[112:115], v[36:39]
	v_mfma_f32_16x16x32_bf16 v[24:27], v[84:87], v[112:115], v[24:27]
	v_mfma_f32_16x16x32_bf16 v[20:23], v[90:93], v[112:115], v[20:23]
	v_mfma_f32_16x16x32_bf16 v[16:19], v[108:111], v[112:115], v[16:19]
	v_mfma_f32_16x16x32_bf16 v[12:15], v[80:83], v[116:119], v[12:15]
	v_mfma_f32_16x16x32_bf16 v[8:11], v[84:87], v[116:119], v[8:11]
	v_mfma_f32_16x16x32_bf16 v[4:7], v[90:93], v[116:119], v[4:7]
	v_mfma_f32_16x16x32_bf16 v[0:3], v[108:111], v[116:119], v[0:3]
	v_mfma_f32_16x16x32_bf16 v[28:31], v[80:83], v[120:123], v[28:31]
	v_mfma_f32_16x16x32_bf16 v[32:35], v[84:87], v[120:123], v[32:35]
	v_mfma_f32_16x16x32_bf16 v[40:43], v[90:93], v[120:123], v[40:43]
	v_mfma_f32_16x16x32_bf16 v[44:47], v[108:111], v[120:123], v[44:47]
	v_mfma_f32_16x16x32_bf16 v[48:51], v[80:83], v[124:127], v[48:51]
	v_mfma_f32_16x16x32_bf16 v[52:55], v[84:87], v[124:127], v[52:55]
	v_mfma_f32_16x16x32_bf16 v[56:59], v[90:93], v[124:127], v[56:59]
	v_mfma_f32_16x16x32_bf16 v[60:63], v[108:111], v[124:127], v[60:63]
	s_waitcnt vmcnt(16)
	v_mfma_f32_16x16x32_bf16 v[36:39], v[128:131], v[144:147], v[36:39]
	v_mfma_f32_16x16x32_bf16 v[24:27], v[132:135], v[144:147], v[24:27]
	v_mfma_f32_16x16x32_bf16 v[20:23], v[136:139], v[144:147], v[20:23]
	v_mfma_f32_16x16x32_bf16 v[16:19], v[140:143], v[144:147], v[16:19]
	v_mfma_f32_16x16x32_bf16 v[12:15], v[128:131], v[158:161], v[12:15]
	v_mfma_f32_16x16x32_bf16 v[8:11], v[132:135], v[158:161], v[8:11]
	v_mfma_f32_16x16x32_bf16 v[4:7], v[136:139], v[158:161], v[4:7]
	v_mfma_f32_16x16x32_bf16 v[0:3], v[140:143], v[158:161], v[0:3]
	v_mfma_f32_16x16x32_bf16 v[28:31], v[128:131], v[162:165], v[28:31]
	v_mfma_f32_16x16x32_bf16 v[32:35], v[132:135], v[162:165], v[32:35]
	v_mfma_f32_16x16x32_bf16 v[40:43], v[136:139], v[162:165], v[40:43]
	v_mfma_f32_16x16x32_bf16 v[44:47], v[140:143], v[162:165], v[44:47]
	v_mfma_f32_16x16x32_bf16 v[48:51], v[128:131], v[166:169], v[48:51]
	v_mfma_f32_16x16x32_bf16 v[52:55], v[132:135], v[166:169], v[52:55]
	v_mfma_f32_16x16x32_bf16 v[56:59], v[136:139], v[166:169], v[56:59]
	v_mfma_f32_16x16x32_bf16 v[60:63], v[140:143], v[166:169], v[60:63]
	s_waitcnt vmcnt(8)
	v_mfma_f32_16x16x32_bf16 v[36:39], v[170:173], v[202:205], v[36:39]
	v_mfma_f32_16x16x32_bf16 v[24:27], v[178:181], v[202:205], v[24:27]
	v_mfma_f32_16x16x32_bf16 v[20:23], v[194:197], v[202:205], v[20:23]
	v_mfma_f32_16x16x32_bf16 v[16:19], v[198:201], v[202:205], v[16:19]
	v_mfma_f32_16x16x32_bf16 v[12:15], v[170:173], v[206:209], v[12:15]
	v_mfma_f32_16x16x32_bf16 v[8:11], v[178:181], v[206:209], v[8:11]
	v_mfma_f32_16x16x32_bf16 v[4:7], v[194:197], v[206:209], v[4:7]
	v_mfma_f32_16x16x32_bf16 v[0:3], v[198:201], v[206:209], v[0:3]
	v_mfma_f32_16x16x32_bf16 v[28:31], v[170:173], v[210:213], v[28:31]
	v_mfma_f32_16x16x32_bf16 v[32:35], v[178:181], v[210:213], v[32:35]
	v_mfma_f32_16x16x32_bf16 v[40:43], v[194:197], v[210:213], v[40:43]
	v_mfma_f32_16x16x32_bf16 v[44:47], v[198:201], v[210:213], v[44:47]
	v_mfma_f32_16x16x32_bf16 v[48:51], v[170:173], v[214:217], v[48:51]
	v_mfma_f32_16x16x32_bf16 v[52:55], v[178:181], v[214:217], v[52:55]
	v_mfma_f32_16x16x32_bf16 v[56:59], v[194:197], v[214:217], v[56:59]
	v_mfma_f32_16x16x32_bf16 v[60:63], v[198:201], v[214:217], v[60:63]
	s_waitcnt vmcnt(0)
	v_mfma_f32_16x16x32_bf16 v[36:39], v[218:221], v[234:237], v[36:39]
	v_mfma_f32_16x16x32_bf16 v[24:27], v[222:225], v[234:237], v[24:27]
	v_mfma_f32_16x16x32_bf16 v[20:23], v[226:229], v[234:237], v[20:23]
	v_mfma_f32_16x16x32_bf16 v[16:19], v[230:233], v[234:237], v[16:19]
	v_mfma_f32_16x16x32_bf16 v[12:15], v[218:221], v[238:241], v[12:15]
	v_mfma_f32_16x16x32_bf16 v[8:11], v[222:225], v[238:241], v[8:11]
	v_mfma_f32_16x16x32_bf16 v[4:7], v[226:229], v[238:241], v[4:7]
	v_mfma_f32_16x16x32_bf16 v[0:3], v[230:233], v[238:241], v[0:3]
	v_mfma_f32_16x16x32_bf16 v[28:31], v[218:221], v[242:245], v[28:31]
	v_mfma_f32_16x16x32_bf16 v[32:35], v[222:225], v[242:245], v[32:35]
	v_mfma_f32_16x16x32_bf16 v[40:43], v[226:229], v[242:245], v[40:43]
	v_mfma_f32_16x16x32_bf16 v[44:47], v[230:233], v[242:245], v[44:47]
	v_mfma_f32_16x16x32_bf16 v[48:51], v[218:221], v[246:249], v[48:51]
	v_mfma_f32_16x16x32_bf16 v[52:55], v[222:225], v[246:249], v[52:55]
	v_mfma_f32_16x16x32_bf16 v[56:59], v[226:229], v[246:249], v[56:59]
	v_mfma_f32_16x16x32_bf16 v[60:63], v[230:233], v[246:249], v[60:63]
	s_barrier
	ds_write_b128 v105, v[36:39]
	ds_write_b128 v105, v[24:27] offset:64
	ds_write_b128 v105, v[20:23] offset:128
	ds_write_b128 v105, v[16:19] offset:192
	ds_write_b128 v105, v[12:15] offset:4352
	ds_write_b128 v105, v[8:11] offset:4416
	ds_write_b128 v105, v[4:7] offset:4480
	ds_write_b128 v105, v[0:3] offset:4544
	ds_write_b128 v105, v[28:31] offset:8704
	ds_write_b128 v105, v[32:35] offset:8768
	ds_write_b128 v105, v[40:43] offset:8832
	ds_write_b128 v105, v[44:47] offset:8896
	ds_write_b128 v106, v[48:51]
	ds_write_b128 v106, v[52:55] offset:64
	ds_write_b128 v106, v[56:59] offset:128
	ds_write_b128 v106, v[60:63] offset:192
	v_add_u32_e32 v0, s18, v94
	v_add_u32_e32 v90, 0x4000, v0
	v_ashrrev_i32_e32 v91, 31, v90
	v_lshlrev_b64 v[0:1], 6, v[90:91]
	v_lshl_add_u64 v[0:1], s[40:41], 0, v[0:1]
	s_waitcnt lgkmcnt(0)
	s_barrier
	flat_load_dwordx4 v[12:15], v[0:1]
	flat_load_dwordx4 v[8:11], v[0:1] offset:16
	flat_load_dwordx4 v[4:7], v[0:1] offset:32
	s_nop 0
	flat_load_dwordx4 v[0:3], v[0:1] offset:48
	ds_read_b128 v[84:87], v96
	ds_read_b128 v[80:83], v96 offset:16
	ds_read_b128 v[76:79], v96 offset:17408
	ds_read_b128 v[72:75], v96 offset:17424
	ds_read_b128 v[68:71], v96 offset:34816
	ds_read_b128 v[64:67], v96 offset:34832
	ds_read_b128 v[60:63], v96 offset:52224
	ds_read_b128 v[56:59], v96 offset:52240
	ds_read_b128 v[52:55], v97
	ds_read_b128 v[48:51], v98
	ds_read_b128 v[44:47], v99
	ds_read_b128 v[40:43], v100
	ds_read_b128 v[36:39], v101
	ds_read_b128 v[32:35], v102
	ds_read_b128 v[20:23], v103
	ds_read_b128 v[16:19], v104
	s_lshl_b32 s18, s23, 2
	s_andn2_b32 s18, s18, 63
	v_or_b32_e32 v92, s18, v95
	s_and_b64 vcc, exec, s[6:7]
	v_ashrrev_i32_e32 v93, 31, v92
	s_cbranch_vccz .LBB0_708
	v_lshl_add_u64 v[28:29], v[92:93], 2, s[50:51]
	global_load_dwordx4 v[24:27], v[28:29], off
	s_nop 0
	global_load_dwordx4 v[28:31], v[28:29], off offset:16
	s_branch .LBB0_709

.LBB0_744:
	s_and_b32 s22, s25, 0xffffffc0
	v_or_b32_e32 v2, s22, v193
	v_lshlrev_b32_e32 v4, 1, v2
	v_or_b32_e32 v5, 0x60, v4
	s_waitcnt lgkmcnt(0)
	v_mov_b64_e32 v[0:1], s[10:11]
	v_mad_u64_u32 v[64:65], s[22:23], s61, v5, v[0:1]
	v_or_b32_e32 v5, 64, v4
	v_or_b32_e32 v4, 32, v4
	v_mad_u64_u32 v[66:67], s[22:23], s61, v5, v[0:1]
	v_mad_u64_u32 v[68:69], s[22:23], s61, v4, v[0:1]
	v_mad_i64_i32 v[70:71], s[22:23], s24, v2, v[0:1]
	s_lshl_b32 s22, s52, 6
	s_and_b32 s22, s22, 0x3c0
	v_or_b32_e32 v0, s22, v193
	v_mul_u32_u24_e32 v152, s61, v0
	v_lshl_add_u64 v[0:1], s[8:9], 0, v[152:153]
	v_lshlrev_b64 v[0:1], 1, v[0:1]
	v_ashrrev_i32_e32 v3, 31, v2
	v_lshl_add_u64 v[72:73], s[14:15], 0, v[0:1]
	v_lshl_add_u64 v[74:75], s[16:17], 0, v[0:1]
	v_lshl_add_u64 v[76:77], s[18:19], 0, v[0:1]
	v_lshlrev_b32_e32 v152, 1, v152
	v_mov_b32_e32 v0, 0
	v_mad_i32_i24 v65, s61, v3, v65
	v_mad_i32_i24 v67, s61, v3, v67
	v_mad_i32_i24 v69, s61, v3, v69
	v_lshl_add_u64 v[78:79], s[20:21], 0, v[152:153]
	s_mov_b32 s23, s0
	v_mov_b32_e32 v1, v0
	v_mov_b32_e32 v2, v0
	v_mov_b32_e32 v3, v0
	v_mov_b32_e32 v4, v0
	v_mov_b32_e32 v5, v0
	v_mov_b32_e32 v6, v0
	v_mov_b32_e32 v7, v0
	v_mov_b32_e32 v8, v0
	v_mov_b32_e32 v9, v0
	v_mov_b32_e32 v10, v0
	v_mov_b32_e32 v11, v0
	v_mov_b32_e32 v12, v0
	v_mov_b32_e32 v13, v0
	v_mov_b32_e32 v14, v0
	v_mov_b32_e32 v15, v0
	v_mov_b32_e32 v16, v0
	v_mov_b32_e32 v17, v0
	v_mov_b32_e32 v18, v0
	v_mov_b32_e32 v19, v0
	v_mov_b32_e32 v20, v0
	v_mov_b32_e32 v21, v0
	v_mov_b32_e32 v22, v0
	v_mov_b32_e32 v23, v0
	v_mov_b32_e32 v24, v0
	v_mov_b32_e32 v25, v0
	v_mov_b32_e32 v26, v0
	v_mov_b32_e32 v27, v0
	v_mov_b32_e32 v36, v0
	v_mov_b32_e32 v37, v0
	v_mov_b32_e32 v38, v0
	v_mov_b32_e32 v39, v0
	v_mov_b32_e32 v28, v0
	v_mov_b32_e32 v29, v0
	v_mov_b32_e32 v30, v0
	v_mov_b32_e32 v31, v0
	v_mov_b32_e32 v32, v0
	v_mov_b32_e32 v33, v0
	v_mov_b32_e32 v34, v0
	v_mov_b32_e32 v35, v0
	v_mov_b32_e32 v40, v0
	v_mov_b32_e32 v41, v0
	v_mov_b32_e32 v42, v0
	v_mov_b32_e32 v43, v0
	v_mov_b32_e32 v44, v0
	v_mov_b32_e32 v45, v0
	v_mov_b32_e32 v46, v0
	v_mov_b32_e32 v47, v0
	v_mov_b32_e32 v48, v0
	v_mov_b32_e32 v49, v0
	v_mov_b32_e32 v50, v0
	v_mov_b32_e32 v51, v0
	v_mov_b32_e32 v52, v0
	v_mov_b32_e32 v53, v0
	v_mov_b32_e32 v54, v0
	v_mov_b32_e32 v55, v0
	v_mov_b32_e32 v56, v0
	v_mov_b32_e32 v57, v0
	v_mov_b32_e32 v58, v0
	v_mov_b32_e32 v59, v0
	v_mov_b32_e32 v60, v0
	v_mov_b32_e32 v61, v0
	v_mov_b32_e32 v62, v0
	v_mov_b32_e32 v63, v0
	v_lshl_add_u64 v[70:71], v[70:71], 0, v[80:81]
	v_lshl_add_u64 v[68:69], v[68:69], 0, v[80:81]
	v_lshl_add_u64 v[66:67], v[66:67], 0, v[80:81]
	v_lshl_add_u64 v[64:65], v[64:65], 0, v[80:81]
	v_lshl_add_u64 v[78:79], v[78:79], 0, v[80:81]
	v_lshl_add_u64 v[76:77], v[76:77], 0, v[80:81]
	v_lshl_add_u64 v[74:75], v[74:75], 0, v[80:81]
	v_lshl_add_u64 v[72:73], v[72:73], 0, v[80:81]
	v_mov_b32_e32 v250, 0x100
	v_mov_b32_e32 v251, 0
	global_load_dwordx4 v[82:85], v[70:71], off
	global_load_dwordx4 v[104:107], v[68:69], off
	global_load_dwordx4 v[108:111], v[66:67], off
	global_load_dwordx4 v[112:115], v[64:65], off
	global_load_dwordx4 v[116:119], v[78:79], off
	global_load_dwordx4 v[120:123], v[76:77], off
	global_load_dwordx4 v[124:127], v[74:75], off
	global_load_dwordx4 v[128:131], v[72:73], off
	global_load_dwordx4 v[132:135], v[70:71], off offset:64
	global_load_dwordx4 v[136:139], v[68:69], off offset:64
	global_load_dwordx4 v[140:143], v[66:67], off offset:64
	global_load_dwordx4 v[144:147], v[64:65], off offset:64
	global_load_dwordx4 v[158:161], v[78:79], off offset:64
	global_load_dwordx4 v[162:165], v[76:77], off offset:64
	global_load_dwordx4 v[166:169], v[74:75], off offset:64
	global_load_dwordx4 v[170:173], v[72:73], off offset:64
	global_load_dwordx4 v[174:177], v[70:71], off offset:128
	global_load_dwordx4 v[178:181], v[68:69], off offset:128
	global_load_dwordx4 v[194:197], v[66:67], off offset:128
	global_load_dwordx4 v[198:201], v[64:65], off offset:128
	global_load_dwordx4 v[202:205], v[78:79], off offset:128
	global_load_dwordx4 v[206:209], v[76:77], off offset:128
	global_load_dwordx4 v[210:213], v[74:75], off offset:128
	global_load_dwordx4 v[214:217], v[72:73], off offset:128
	global_load_dwordx4 v[218:221], v[70:71], off offset:192
	global_load_dwordx4 v[222:225], v[68:69], off offset:192
	global_load_dwordx4 v[226:229], v[66:67], off offset:192
	global_load_dwordx4 v[230:233], v[64:65], off offset:192
	global_load_dwordx4 v[234:237], v[78:79], off offset:192
	global_load_dwordx4 v[238:241], v[76:77], off offset:192
	global_load_dwordx4 v[242:245], v[74:75], off offset:192
	global_load_dwordx4 v[246:249], v[72:73], off offset:192
	s_lshr_b32 s23, s23, 2
	s_add_i32 s23, s23, -1
.Lgsr_loop:
	s_cmp_eq_u32 s23, 0
	s_cbranch_scc1 .Lgsr_tail
	s_waitcnt vmcnt(24)
	v_mfma_f32_16x16x32_bf16 v[36:39], v[82:85], v[116:119], v[36:39]
	v_mfma_f32_16x16x32_bf16 v[24:27], v[104:107], v[116:119], v[24:27]
	v_mfma_f32_16x16x32_bf16 v[20:23], v[108:111], v[116:119], v[20:23]
	v_mfma_f32_16x16x32_bf16 v[16:19], v[112:115], v[116:119], v[16:19]
	v_mfma_f32_16x16x32_bf16 v[12:15], v[82:85], v[120:123], v[12:15]
	v_mfma_f32_16x16x32_bf16 v[8:11], v[104:107], v[120:123], v[8:11]
	v_mfma_f32_16x16x32_bf16 v[4:7], v[108:111], v[120:123], v[4:7]
	v_mfma_f32_16x16x32_bf16 v[0:3], v[112:115], v[120:123], v[0:3]
	v_mfma_f32_16x16x32_bf16 v[28:31], v[82:85], v[124:127], v[28:31]
	v_mfma_f32_16x16x32_bf16 v[32:35], v[104:107], v[124:127], v[32:35]
	v_mfma_f32_16x16x32_bf16 v[40:43], v[108:111], v[124:127], v[40:43]
	v_mfma_f32_16x16x32_bf16 v[44:47], v[112:115], v[124:127], v[44:47]
	v_mfma_f32_16x16x32_bf16 v[48:51], v[82:85], v[128:131], v[48:51]
	v_mfma_f32_16x16x32_bf16 v[52:55], v[104:107], v[128:131], v[52:55]
	v_mfma_f32_16x16x32_bf16 v[56:59], v[108:111], v[128:131], v[56:59]
	v_mfma_f32_16x16x32_bf16 v[60:63], v[112:115], v[128:131], v[60:63]
	global_load_dwordx4 v[82:85], v[70:71], off offset:256
	global_load_dwordx4 v[104:107], v[68:69], off offset:256
	global_load_dwordx4 v[108:111], v[66:67], off offset:256
	global_load_dwordx4 v[112:115], v[64:65], off offset:256
	global_load_dwordx4 v[116:119], v[78:79], off offset:256
	global_load_dwordx4 v[120:123], v[76:77], off offset:256
	global_load_dwordx4 v[124:127], v[74:75], off offset:256
	global_load_dwordx4 v[128:131], v[72:73], off offset:256
	s_waitcnt vmcnt(24)
	v_mfma_f32_16x16x32_bf16 v[36:39], v[132:135], v[158:161], v[36:39]
	v_mfma_f32_16x16x32_bf16 v[24:27], v[136:139], v[158:161], v[24:27]
	v_mfma_f32_16x16x32_bf16 v[20:23], v[140:143], v[158:161], v[20:23]
	v_mfma_f32_16x16x32_bf16 v[16:19], v[144:147], v[158:161], v[16:19]
	v_mfma_f32_16x16x32_bf16 v[12:15], v[132:135], v[162:165], v[12:15]
	v_mfma_f32_16x16x32_bf16 v[8:11], v[136:139], v[162:165], v[8:11]
	v_mfma_f32_16x16x32_bf16 v[4:7], v[140:143], v[162:165], v[4:7]
	v_mfma_f32_16x16x32_bf16 v[0:3], v[144:147], v[162:165], v[0:3]
	v_mfma_f32_16x16x32_bf16 v[28:31], v[132:135], v[166:169], v[28:31]
	v_mfma_f32_16x16x32_bf16 v[32:35], v[136:139], v[166:169], v[32:35]
	v_mfma_f32_16x16x32_bf16 v[40:43], v[140:143], v[166:169], v[40:43]
	v_mfma_f32_16x16x32_bf16 v[44:47], v[144:147], v[166:169], v[44:47]
	v_mfma_f32_16x16x32_bf16 v[48:51], v[132:135], v[170:173], v[48:51]
	v_mfma_f32_16x16x32_bf16 v[52:55], v[136:139], v[170:173], v[52:55]
	v_mfma_f32_16x16x32_bf16 v[56:59], v[140:143], v[170:173], v[56:59]
	v_mfma_f32_16x16x32_bf16 v[60:63], v[144:147], v[170:173], v[60:63]
	global_load_dwordx4 v[132:135], v[70:71], off offset:320
	global_load_dwordx4 v[136:139], v[68:69], off offset:320
	global_load_dwordx4 v[140:143], v[66:67], off offset:320
	global_load_dwordx4 v[144:147], v[64:65], off offset:320
	global_load_dwordx4 v[158:161], v[78:79], off offset:320
	global_load_dwordx4 v[162:165], v[76:77], off offset:320
	global_load_dwordx4 v[166:169], v[74:75], off offset:320
	global_load_dwordx4 v[170:173], v[72:73], off offset:320
	s_waitcnt vmcnt(24)
	v_mfma_f32_16x16x32_bf16 v[36:39], v[174:177], v[202:205], v[36:39]
	v_mfma_f32_16x16x32_bf16 v[24:27], v[178:181], v[202:205], v[24:27]
	v_mfma_f32_16x16x32_bf16 v[20:23], v[194:197], v[202:205], v[20:23]
	v_mfma_f32_16x16x32_bf16 v[16:19], v[198:201], v[202:205], v[16:19]
	v_mfma_f32_16x16x32_bf16 v[12:15], v[174:177], v[206:209], v[12:15]
	v_mfma_f32_16x16x32_bf16 v[8:11], v[178:181], v[206:209], v[8:11]
	v_mfma_f32_16x16x32_bf16 v[4:7], v[194:197], v[206:209], v[4:7]
	v_mfma_f32_16x16x32_bf16 v[0:3], v[198:201], v[206:209], v[0:3]
	v_mfma_f32_16x16x32_bf16 v[28:31], v[174:177], v[210:213], v[28:31]
	v_mfma_f32_16x16x32_bf16 v[32:35], v[178:181], v[210:213], v[32:35]
	v_mfma_f32_16x16x32_bf16 v[40:43], v[194:197], v[210:213], v[40:43]
	v_mfma_f32_16x16x32_bf16 v[44:47], v[198:201], v[210:213], v[44:47]
	v_mfma_f32_16x16x32_bf16 v[48:51], v[174:177], v[214:217], v[48:51]
	v_mfma_f32_16x16x32_bf16 v[52:55], v[178:181], v[214:217], v[52:55]
	v_mfma_f32_16x16x32_bf16 v[56:59], v[194:197], v[214:217], v[56:59]
	v_mfma_f32_16x16x32_bf16 v[60:63], v[198:201], v[214:217], v[60:63]
	global_load_dwordx4 v[174:177], v[70:71], off offset:384
	global_load_dwordx4 v[178:181], v[68:69], off offset:384
	global_load_dwordx4 v[194:197], v[66:67], off offset:384
	global_load_dwordx4 v[198:201], v[64:65], off offset:384
	global_load_dwordx4 v[202:205], v[78:79], off offset:384
	global_load_dwordx4 v[206:209], v[76:77], off offset:384
	global_load_dwordx4 v[210:213], v[74:75], off offset:384
	global_load_dwordx4 v[214:217], v[72:73], off offset:384
	s_waitcnt vmcnt(24)
	v_mfma_f32_16x16x32_bf16 v[36:39], v[218:221], v[234:237], v[36:39]
	v_mfma_f32_16x16x32_bf16 v[24:27], v[222:225], v[234:237], v[24:27]
	v_mfma_f32_16x16x32_bf16 v[20:23], v[226:229], v[234:237], v[20:23]
	v_mfma_f32_16x16x32_bf16 v[16:19], v[230:233], v[234:237], v[16:19]
	v_mfma_f32_16x16x32_bf16 v[12:15], v[218:221], v[238:241], v[12:15]
	v_mfma_f32_16x16x32_bf16 v[8:11], v[222:225], v[238:241], v[8:11]
	v_mfma_f32_16x16x32_bf16 v[4:7], v[226:229], v[238:241], v[4:7]
	v_mfma_f32_16x16x32_bf16 v[0:3], v[230:233], v[238:241], v[0:3]
	v_mfma_f32_16x16x32_bf16 v[28:31], v[218:221], v[242:245], v[28:31]
	v_mfma_f32_16x16x32_bf16 v[32:35], v[222:225], v[242:245], v[32:35]
	v_mfma_f32_16x16x32_bf16 v[40:43], v[226:229], v[242:245], v[40:43]
	v_mfma_f32_16x16x32_bf16 v[44:47], v[230:233], v[242:245], v[44:47]
	v_mfma_f32_16x16x32_bf16 v[48:51], v[218:221], v[246:249], v[48:51]
	v_mfma_f32_16x16x32_bf16 v[52:55], v[222:225], v[246:249], v[52:55]
	v_mfma_f32_16x16x32_bf16 v[56:59], v[226:229], v[246:249], v[56:59]
	v_mfma_f32_16x16x32_bf16 v[60:63], v[230:233], v[246:249], v[60:63]
	global_load_dwordx4 v[218:221], v[70:71], off offset:448
	global_load_dwordx4 v[222:225], v[68:69], off offset:448
	global_load_dwordx4 v[226:229], v[66:67], off offset:448
	global_load_dwordx4 v[230:233], v[64:65], off offset:448
	global_load_dwordx4 v[234:237], v[78:79], off offset:448
	global_load_dwordx4 v[238:241], v[76:77], off offset:448
	global_load_dwordx4 v[242:245], v[74:75], off offset:448
	global_load_dwordx4 v[246:249], v[72:73], off offset:448
	v_lshl_add_u64 v[70:71], v[70:71], 0, v[250:251]
	v_lshl_add_u64 v[68:69], v[68:69], 0, v[250:251]
	v_lshl_add_u64 v[66:67], v[66:67], 0, v[250:251]
	v_lshl_add_u64 v[64:65], v[64:65], 0, v[250:251]
	v_lshl_add_u64 v[78:79], v[78:79], 0, v[250:251]
	v_lshl_add_u64 v[76:77], v[76:77], 0, v[250:251]
	v_lshl_add_u64 v[74:75], v[74:75], 0, v[250:251]
	v_lshl_add_u64 v[72:73], v[72:73], 0, v[250:251]
	s_add_i32 s23, s23, -1
	s_branch .Lgsr_loop
.Lgsr_tail:
	s_waitcnt vmcnt(24)
	v_mfma_f32_16x16x32_bf16 v[36:39], v[82:85], v[116:119], v[36:39]
	v_mfma_f32_16x16x32_bf16 v[24:27], v[104:107], v[116:119], v[24:27]
	v_mfma_f32_16x16x32_bf16 v[20:23], v[108:111], v[116:119], v[20:23]
	v_mfma_f32_16x16x32_bf16 v[16:19], v[112:115], v[116:119], v[16:19]
	v_mfma_f32_16x16x32_bf16 v[12:15], v[82:85], v[120:123], v[12:15]
	v_mfma_f32_16x16x32_bf16 v[8:11], v[104:107], v[120:123], v[8:11]
	v_mfma_f32_16x16x32_bf16 v[4:7], v[108:111], v[120:123], v[4:7]
	v_mfma_f32_16x16x32_bf16 v[0:3], v[112:115], v[120:123], v[0:3]
	v_mfma_f32_16x16x32_bf16 v[28:31], v[82:85], v[124:127], v[28:31]
	v_mfma_f32_16x16x32_bf16 v[32:35], v[104:107], v[124:127], v[32:35]
	v_mfma_f32_16x16x32_bf16 v[40:43], v[108:111], v[124:127], v[40:43]
	v_mfma_f32_16x16x32_bf16 v[44:47], v[112:115], v[124:127], v[44:47]
	v_mfma_f32_16x16x32_bf16 v[48:51], v[82:85], v[128:131], v[48:51]
	v_mfma_f32_16x16x32_bf16 v[52:55], v[104:107], v[128:131], v[52:55]
	v_mfma_f32_16x16x32_bf16 v[56:59], v[108:111], v[128:131], v[56:59]
	v_mfma_f32_16x16x32_bf16 v[60:63], v[112:115], v[128:131], v[60:63]
	s_waitcnt vmcnt(16)
	v_mfma_f32_16x16x32_bf16 v[36:39], v[132:135], v[158:161], v[36:39]
	v_mfma_f32_16x16x32_bf16 v[24:27], v[136:139], v[158:161], v[24:27]
	v_mfma_f32_16x16x32_bf16 v[20:23], v[140:143], v[158:161], v[20:23]
	v_mfma_f32_16x16x32_bf16 v[16:19], v[144:147], v[158:161], v[16:19]
	v_mfma_f32_16x16x32_bf16 v[12:15], v[132:135], v[162:165], v[12:15]
	v_mfma_f32_16x16x32_bf16 v[8:11], v[136:139], v[162:165], v[8:11]
	v_mfma_f32_16x16x32_bf16 v[4:7], v[140:143], v[162:165], v[4:7]
	v_mfma_f32_16x16x32_bf16 v[0:3], v[144:147], v[162:165], v[0:3]
	v_mfma_f32_16x16x32_bf16 v[28:31], v[132:135], v[166:169], v[28:31]
	v_mfma_f32_16x16x32_bf16 v[32:35], v[136:139], v[166:169], v[32:35]
	v_mfma_f32_16x16x32_bf16 v[40:43], v[140:143], v[166:169], v[40:43]
	v_mfma_f32_16x16x32_bf16 v[44:47], v[144:147], v[166:169], v[44:47]
	v_mfma_f32_16x16x32_bf16 v[48:51], v[132:135], v[170:173], v[48:51]
	v_mfma_f32_16x16x32_bf16 v[52:55], v[136:139], v[170:173], v[52:55]
	v_mfma_f32_16x16x32_bf16 v[56:59], v[140:143], v[170:173], v[56:59]
	v_mfma_f32_16x16x32_bf16 v[60:63], v[144:147], v[170:173], v[60:63]
	s_waitcnt vmcnt(8)
	v_mfma_f32_16x16x32_bf16 v[36:39], v[174:177], v[202:205], v[36:39]
	v_mfma_f32_16x16x32_bf16 v[24:27], v[178:181], v[202:205], v[24:27]
	v_mfma_f32_16x16x32_bf16 v[20:23], v[194:197], v[202:205], v[20:23]
	v_mfma_f32_16x16x32_bf16 v[16:19], v[198:201], v[202:205], v[16:19]
	v_mfma_f32_16x16x32_bf16 v[12:15], v[174:177], v[206:209], v[12:15]
	v_mfma_f32_16x16x32_bf16 v[8:11], v[178:181], v[206:209], v[8:11]
	v_mfma_f32_16x16x32_bf16 v[4:7], v[194:197], v[206:209], v[4:7]
	v_mfma_f32_16x16x32_bf16 v[0:3], v[198:201], v[206:209], v[0:3]
	v_mfma_f32_16x16x32_bf16 v[28:31], v[174:177], v[210:213], v[28:31]
	v_mfma_f32_16x16x32_bf16 v[32:35], v[178:181], v[210:213], v[32:35]
	v_mfma_f32_16x16x32_bf16 v[40:43], v[194:197], v[210:213], v[40:43]
	v_mfma_f32_16x16x32_bf16 v[44:47], v[198:201], v[210:213], v[44:47]
	v_mfma_f32_16x16x32_bf16 v[48:51], v[174:177], v[214:217], v[48:51]
	v_mfma_f32_16x16x32_bf16 v[52:55], v[178:181], v[214:217], v[52:55]
	v_mfma_f32_16x16x32_bf16 v[56:59], v[194:197], v[214:217], v[56:59]
	v_mfma_f32_16x16x32_bf16 v[60:63], v[198:201], v[214:217], v[60:63]
	s_waitcnt vmcnt(0)
	v_mfma_f32_16x16x32_bf16 v[36:39], v[218:221], v[234:237], v[36:39]
	v_mfma_f32_16x16x32_bf16 v[24:27], v[222:225], v[234:237], v[24:27]
	v_mfma_f32_16x16x32_bf16 v[20:23], v[226:229], v[234:237], v[20:23]
	v_mfma_f32_16x16x32_bf16 v[16:19], v[230:233], v[234:237], v[16:19]
	v_mfma_f32_16x16x32_bf16 v[12:15], v[218:221], v[238:241], v[12:15]
	v_mfma_f32_16x16x32_bf16 v[8:11], v[222:225], v[238:241], v[8:11]
	v_mfma_f32_16x16x32_bf16 v[4:7], v[226:229], v[238:241], v[4:7]
	v_mfma_f32_16x16x32_bf16 v[0:3], v[230:233], v[238:241], v[0:3]
	v_mfma_f32_16x16x32_bf16 v[28:31], v[218:221], v[242:245], v[28:31]
	v_mfma_f32_16x16x32_bf16 v[32:35], v[222:225], v[242:245], v[32:35]
	v_mfma_f32_16x16x32_bf16 v[40:43], v[226:229], v[242:245], v[40:43]
	v_mfma_f32_16x16x32_bf16 v[44:47], v[230:233], v[242:245], v[44:47]
	v_mfma_f32_16x16x32_bf16 v[48:51], v[218:221], v[246:249], v[48:51]
	v_mfma_f32_16x16x32_bf16 v[52:55], v[222:225], v[246:249], v[52:55]
	v_mfma_f32_16x16x32_bf16 v[56:59], v[226:229], v[246:249], v[56:59]
	v_mfma_f32_16x16x32_bf16 v[60:63], v[230:233], v[246:249], v[60:63]
	s_barrier
	ds_write_b128 v102, v[36:39]
	ds_write_b128 v102, v[24:27] offset:64
	ds_write_b128 v102, v[20:23] offset:128
	ds_write_b128 v102, v[16:19] offset:192
	ds_write_b128 v102, v[12:15] offset:4352
	ds_write_b128 v102, v[8:11] offset:4416
	ds_write_b128 v102, v[4:7] offset:4480
	ds_write_b128 v102, v[0:3] offset:4544
	ds_write_b128 v102, v[28:31] offset:8704
	ds_write_b128 v102, v[32:35] offset:8768
	ds_write_b128 v102, v[40:43] offset:8832
	ds_write_b128 v102, v[44:47] offset:8896
	ds_write_b128 v103, v[48:51]
	ds_write_b128 v103, v[52:55] offset:64
	ds_write_b128 v103, v[56:59] offset:128
	ds_write_b128 v103, v[60:63] offset:192
	s_waitcnt lgkmcnt(0)
	s_barrier
	ds_read_b128 v[68:71], v90
	ds_read_b128 v[64:67], v90 offset:16
	ds_read_b128 v[60:63], v90 offset:17408
	ds_read_b128 v[56:59], v90 offset:17424
	ds_read_b128 v[52:55], v90 offset:34816
	ds_read_b128 v[48:51], v90 offset:34832
	ds_read_b128 v[44:47], v90 offset:52224
	ds_read_b128 v[40:43], v90 offset:52240
	ds_read_b128 v[36:39], v94
	ds_read_b128 v[32:35], v95
	ds_read_b128 v[28:31], v96
	ds_read_b128 v[24:27], v97
	ds_read_b128 v[20:23], v98
	ds_read_b128 v[12:15], v99
	ds_read_b128 v[4:7], v100
	ds_read_b128 v[0:3], v101
	s_lshl_b32 s23, s52, 2
	s_andn2_b32 s23, s23, 63
	v_or_b32_e32 v82, s23, v89
	s_and_b64 vcc, exec, s[12:13]
	v_ashrrev_i32_e32 v83, 31, v82
	s_cbranch_vccz .LBB0_756
	v_lshl_add_u64 v[8:9], v[82:83], 2, s[50:51]
	global_load_dwordx4 v[16:19], v[8:9], off
	s_nop 0
	global_load_dwordx4 v[8:11], v[8:9], off offset:16
	v_add_u32_e32 v72, s22, v88
	s_and_b64 vcc, exec, s[6:7]
	v_add_u32_e32 v84, 0x4000, v72
	s_cbranch_vccnz .LBB0_757
